# combo9 = combo8 + split-phase first grid sync: workgroups >= 8 arrive, run the weight-conversion phase, and only then wait/acquire/post
# speedup vs baseline: 1.0048x; 1.0048x over previous
; __global__ void __launch_bounds__(512, 2) mk_fwd(Args a) {
;     ...
;         if (ph + 1 < a.ph_hi) {
;             if (ph == a.ph_lo) { grid.sync(); bar = xcd_barrier_post((unsigned*)(a.ws + WS_BAR), bst); }
.LBB0_658:
	s_mov_b32 s100, s35
	s_cmp_lg_u32 s35, 1
	s_cbranch_scc1 .Ldw_done
	v_readlane_b32 s0, v254, 44
	s_nop 3
	s_cmp_lt_u32 s0, 8
	s_cbranch_scc1 .Ldw_done
	v_cmp_eq_u32_e64 s[98:99], 0, v232
	s_nop 3
	s_and_saveexec_b64 s[0:1], s[98:99]
	s_cbranch_execz .Ldw_join
	v_readlane_b32 s98, v254, 0
	v_readlane_b32 s99, v254, 1
	s_nop 3
	s_load_dwordx2 s[98:99], s[98:99], 0x58
	v_mov_b32_e32 v1, 0x23ff8
	ds_read_b32 v0, v1
	s_waitcnt lgkmcnt(0)
.Ldw_spin:
	global_load_dword v1, v129, s[98:99] offset:32 sc1
	s_waitcnt vmcnt(0)
	v_and_b32_e32 v1, 0xffff0000, v1
	v_cmp_eq_u32_e32 vcc, v1, v0
	s_cbranch_vccz .Ldw_released
	s_sleep 1
	s_branch .Ldw_spin
.Ldw_released:
	buffer_inv sc1
	v_readlane_b32 s98, v254, 39
	s_nop 3
	s_lshl_b32 s98, s98, 8
	v_mov_b32_e32 v0, s98
	v_readlane_b32 s98, v254, 8
	v_readlane_b32 s99, v254, 9
	s_nop 4
	global_atomic_add v0, v233, s[98:99] offset:1024
	s_waitcnt vmcnt(0)

; __global__ void __launch_bounds__(512, 2) mk_fwd(Args a) {
;     ...
;         if (ph + 1 < a.ph_hi) {
;             if (ph == a.ph_lo) { grid.sync(); bar = xcd_barrier_post((unsigned*)(a.ws + WS_BAR), bst); }
.Ldw_done:
	s_cmp_lg_u32 s35, 1
	s_cbranch_scc1 .Lmap_chk_done
	v_cmp_eq_u32_e64 s[98:99], 0, v232
	s_nop 3
	s_and_saveexec_b64 s[0:1], s[98:99]
	s_cbranch_execz .Lmap_skip_atomic
	v_readlane_b32 s98, v254, 44
	s_nop 3
	s_and_b32 s98, s98, 7
	s_lshl_b32 s98, s98, 2
	v_mov_b32_e32 v0, s98
	v_readlane_b32 s98, v254, 39
	s_nop 3
	s_lshl_b32 s98, 1, s98
	v_mov_b32_e32 v1, s98
	v_readlane_b32 s98, v254, 8
	v_readlane_b32 s99, v254, 9
	s_nop 4
	global_atomic_or v0, v1, s[98:99] offset:768

; __global__ void __launch_bounds__(512, 2) mk_fwd(Args a) {
;     ...
;             if (ph == a.ph_lo) { grid.sync(); bar = xcd_barrier_post((unsigned*)(a.ws + WS_BAR), bst); }
.LBB0_722:
	s_or_b64 exec, exec, s[6:7]
	global_load_dword v2, v129, s[4:5] offset:32 sc1
	v_and_b32_e32 v0, 0xffff0000, v1
	v_mov_b32_e32 v3, 0x23ff8
	ds_write_b32 v3, v0
	s_waitcnt lgkmcnt(0)
	v_readlane_b32 s6, v254, 44
	s_nop 3
	s_cmp_lt_u32 s6, 8
	s_cbranch_scc1 .Lcg_wait_now
	s_waitcnt vmcnt(0)
	s_branch .LBB0_726
.Lcg_wait_now:
	s_waitcnt vmcnt(0)
	v_and_b32_e32 v1, 0xffff0000, v2
	v_cmp_eq_u32_e32 vcc, v1, v0
	s_and_b64 exec, exec, vcc
	s_cbranch_execz .LBB0_725
	s_mov_b64 s[6:7], 0

; #define LAS __attribute__((address_space(3)))
; __device__ __forceinline__ unsigned xb_add(unsigned* p, unsigned v) { return __hip_atomic_fetch_add(p, v, __ATOMIC_RELAXED, __HIP_MEMORY_SCOPE_AGENT); }
; __device__ __forceinline__ unsigned xb_xcc_id() { return (unsigned)__builtin_amdgcn_s_getreg((3 << 11) | 20) & 0xFu; }
; __device__ __forceinline__ XcdBarrier xcd_barrier_post(unsigned* bar, volatile LAS unsigned* st) {
;     XcdBarrier b; b.bar = bar; b.x = xb_xcc_id(); b.st = st;
;     if (threadIdx.x == 0) (void)xb_add(&bar[XB_XCNT(b.x)], 1u);
;     return b;
.LBB0_726:
	s_or_b64 exec, exec, s[0:1]
	s_barrier
	s_getreg_b32 s0, hwreg(HW_REG_XCC_ID, 0, 4)
	s_and_b32 s0, s0, 15
	v_writelane_b32 v254, s0, 39
	s_mov_b64 s[0:1], exec
	v_readlane_b32 s4, v254, 40
	v_readlane_b32 s5, v254, 41
	s_and_b64 s[4:5], s[0:1], s[4:5]
	s_xor_b64 s[0:1], s[4:5], s[0:1]
	s_mov_b64 exec, s[4:5]
	s_cbranch_execz .LBB0_5
	v_readlane_b32 s6, v254, 44
	s_nop 3
	s_cmp_lt_u32 s6, 8
	s_cbranch_scc0 .LBB0_5
	s_mov_b64 s[6:7], exec
	v_mbcnt_lo_u32_b32 v0, s6, 0
	v_mbcnt_hi_u32_b32 v0, s7, v0
	v_cmp_eq_u32_e32 vcc, 0, v0
	s_and_saveexec_b64 s[4:5], vcc
	s_xor_b64 s[4:5], exec, s[4:5]
	s_cbranch_execz .LBB0_4
	v_readlane_b32 s8, v254, 39
	s_bcnt1_i32_b64 s6, s[6:7]
	s_lshl_b32 s8, s8, 8
	v_mov_b32_e32 v1, s6
	v_readlane_b32 s6, v254, 8
	v_mov_b32_e32 v0, s8
	v_readlane_b32 s7, v254, 9
	s_nop 4
	global_atomic_add v0, v1, s[6:7] offset:1024
	s_branch .LBB0_4
